# st5 branch-merge epilogue: dedicated straight-line path for the conv/pool/sb units (8 gate loads up front, only the gate sigmoid computed; the common path also computed sigmoid(acc) and selected it aw
# speedup vs baseline: 1.0214x; 1.0214x over previous
.LBB0_8:
	s_or_b64 exec, exec, s[2:3]
	s_waitcnt lgkmcnt(0)
	s_barrier
	s_load_dwordx2 s[44:45], s[0:1], 0xd8
	s_waitcnt lgkmcnt(0)
	s_cmp_ge_i32 s44, s45
	s_cbranch_scc1 .Lexit_near
	s_load_dword s2, s[0:1], 0xe0
	s_lshl_b32 s64, s33, 3
	s_load_dwordx2 s[0:1], s[0:1], 0xc8
	s_lshl_b32 s28, s33, 9
	v_lshrrev_b32_e32 v2, 20, v0
	s_waitcnt lgkmcnt(0)
	s_cmp_lg_u32 s2, 0
	s_cselect_b64 s[30:31], -1, 0
	v_writelane_b32 v253, s0, 5
	s_add_i32 s26, s44, 1
	v_lshrrev_b32_e32 v0, 10, v0
	v_writelane_b32 v253, s1, 6
	s_and_b32 s0, s33, 7
	s_cmp_eq_u32 s0, 0
	s_cselect_b64 s[0:1], -1, 0
	v_writelane_b32 v253, s0, 7
	s_ashr_i32 s53, s33, 31
	v_or_b32_e32 v0, v0, v2
	v_writelane_b32 v253, s1, 8
	s_lshr_b32 s0, s53, 29
	s_add_i32 s0, s33, s0
	s_ashr_i32 s0, s0, 3
	s_cmpk_lg_i32 s33, 0x100
	v_writelane_b32 v253, s0, 9
	s_cselect_b64 s[0:1], -1, 0
	v_writelane_b32 v253, s0, 10
	v_mov_b32_e32 v145, 0
	v_mov_b32_e32 v247, 0x358637bd
	v_writelane_b32 v253, s1, 11
	s_add_u32 s0, s78, 0xdc00000
	s_addc_u32 s1, s79, 0
	v_writelane_b32 v253, s0, 12
	v_mov_b32_e32 v236, 0x2000
	v_mov_b32_e32 v237, 1
	v_writelane_b32 v253, s1, 13
	s_add_u32 s0, s78, 0xdd00000
	s_addc_u32 s1, s79, 0
	v_writelane_b32 v253, s0, 14
	v_mov_b32_e32 v239, 0x9000
	v_mov_b32_e32 v245, 0x3e000000
	v_writelane_b32 v253, s1, 15
	s_add_u32 s0, s78, 0xde00000
	s_addc_u32 s1, s79, 0
	v_writelane_b32 v253, s0, 16
	s_movk_i32 s65, 0x88
	s_mov_b32 s95, 0x20000
	v_writelane_b32 v253, s1, 17
	s_add_u32 s0, s78, 0xda00000
	s_addc_u32 s1, s79, 0
	s_cmp_gt_i32 s33, 64
	v_writelane_b32 v253, s0, 18
	s_cselect_b32 s3, 64, 0
	s_ashr_i32 s29, s28, 31
	v_writelane_b32 v253, s1, 19
	s_sub_i32 s0, s33, s3
	s_lshl_b32 s1, s0, 3
	s_lshl_b32 s0, s0, 9
	v_writelane_b32 v253, s1, 20
	s_cmp_lt_i32 s2, 0
	v_writelane_b32 v253, s0, 21
	s_cselect_b64 s[0:1], -1, 0
	v_writelane_b32 v253, s0, 22
	s_mov_b32 s54, 0x9000
	s_movk_i32 s66, 0x1000
	v_writelane_b32 v253, s1, 23
	s_add_u32 s0, s78, 0x26400000
	v_writelane_b32 v253, s0, 24
	s_addc_u32 s0, s79, 0
	s_add_u32 s34, s78, 0x26400200
	s_addc_u32 s35, s79, 0
	s_add_u32 s36, s78, 0x26400400
	s_addc_u32 s37, s79, 0
	s_add_u32 s24, s78, 0x26400500
	s_addc_u32 s25, s79, 0
	s_add_u32 s16, s78, 0x26400600
	s_addc_u32 s17, s79, 0
	s_add_u32 s18, s78, 0x26400700
	s_addc_u32 s19, s79, 0
	s_add_u32 s20, s78, 0x26400800
	s_addc_u32 s21, s79, 0
	s_add_u32 s22, s78, 0x26400900
	s_addc_u32 s23, s79, 0
	s_add_u32 s42, s78, 0x26400a00
	s_addc_u32 s43, s79, 0
	s_add_u32 s46, s78, 0x26400b00
	s_addc_u32 s47, s79, 0
	s_add_u32 s48, s78, 0x26400c00
	s_addc_u32 s49, s79, 0
	s_add_u32 s60, s78, 0x26400d00
	s_addc_u32 s61, s79, 0
	s_add_u32 s62, s78, 0x26400e00
	s_addc_u32 s63, s79, 0
	s_add_u32 s72, s78, 0x26400f00
	s_addc_u32 s73, s79, 0
	s_add_u32 s82, s78, 0x26401000
	s_addc_u32 s83, s79, 0
	s_add_u32 s84, s78, 0x26401100
	s_addc_u32 s85, s79, 0
	s_add_u32 s86, s78, 0x26401200
	s_addc_u32 s87, s79, 0
	s_add_u32 s88, s78, 0x26401300
	s_addc_u32 s89, s79, 0
	v_writelane_b32 v253, s0, 25
	s_add_u32 s0, s78, 0x26403400
	s_addc_u32 s1, s79, 0
	v_writelane_b32 v253, s0, 26
	s_movk_i32 s69, 0x300
	s_movk_i32 s68, 0x2000
	v_writelane_b32 v253, s1, 27
	s_add_u32 s0, s78, 0x26403500
	s_addc_u32 s1, s79, 0
	s_abs_i32 s2, s33
	v_cvt_f32_u32_e32 v1, s2
	v_writelane_b32 v253, s0, 28
	s_mov_b32 s59, 0x12000
	s_mov_b32 s67, 0x24000
	v_rcp_iflag_f32_e32 v1, v1
	v_writelane_b32 v253, s1, 29
	s_movk_i32 s0, 0x3ff
	v_and_or_b32 v0, v0, s0, v244
	v_mul_f32_e32 v1, 0x4f7ffffe, v1
	v_cvt_u32_f32_e32 v1, v1
	s_sub_i32 s0, 0, s2
	s_mov_b32 s81, 0x2081cea
	s_mov_b32 s74, 0x36000
	v_readfirstlane_b32 s1, v1
	s_mul_i32 s0, s0, s1
	s_mul_hi_u32 s0, s1, s0
	s_add_i32 s0, s1, s0
	v_writelane_b32 v253, s0, 30
	s_mul_hi_u32 s0, s0, 0x5c0
	s_mul_i32 s0, s0, s2
	s_sub_i32 s0, 0x5c0, s0
	s_sub_i32 s1, s0, s2
	s_cmp_ge_u32 s0, s2
	s_cselect_b32 s0, s1, s0
	s_sub_i32 s1, s0, s2
	s_cmp_ge_u32 s0, s2
	v_writelane_b32 v253, s2, 31
	s_cselect_b32 s0, s1, s0
	v_writelane_b32 v253, s0, 32
	s_lshl_b32 s0, s33, 12
	s_lshl_b32 s1, s3, 12
	v_writelane_b32 v253, s3, 33
	s_sub_i32 s0, s0, s1
	v_writelane_b32 v253, s0, 34
	s_mul_i32 s0, s33, 0x11000
	s_mul_hi_i32 s1, s28, 0x88
	v_writelane_b32 v253, s0, 35
	s_movk_i32 s2, 0x3000
	s_mov_b32 s3, 0x22000000
	v_writelane_b32 v253, s1, 36
	s_lshl_b32 s0, s33, 4
	v_writelane_b32 v253, s0, 37
	s_lshl_b32 s0, s33, 10
	v_writelane_b32 v253, s0, 38
	s_lshl_b32 s0, s33, 11
	v_writelane_b32 v253, s0, 39
	s_add_i32 s0, 0, 0x2020c
	v_writelane_b32 v253, s0, 40
	s_add_i32 s0, 0, 0x20208
	v_writelane_b32 v253, s0, 41
	s_add_i32 s0, 0, 0x20210
	v_writelane_b32 v253, s0, 42
	s_add_i32 s0, 0, 0x20000
	v_writelane_b32 v253, s0, 43
	s_add_i32 s0, 0, 0x20020
	v_writelane_b32 v253, s0, 44
	s_add_i32 s0, 0, 0x20080
	v_writelane_b32 v253, s0, 45
	s_add_i32 s0, 0, 0x20090
	v_writelane_b32 v253, s0, 46
	s_add_i32 s0, 0, 0x20048
	v_writelane_b32 v253, s0, 47
	s_add_i32 s0, 0, 0x20028
	v_writelane_b32 v253, s0, 48
	s_add_i32 s0, 0, 0x20008
	v_writelane_b32 v253, s0, 49
	s_add_i32 s0, 0, 0x20010
	v_writelane_b32 v253, s0, 50
	s_add_i32 s0, 0, 0x20018
	v_writelane_b32 v253, s0, 51
	s_add_i32 s0, 0, 0x20058
	v_writelane_b32 v253, s0, 52
	s_add_i32 s0, 0, 0x20068
	v_writelane_b32 v253, s0, 53
	s_add_i32 s0, 0, 0x20078
	v_writelane_b32 v253, s0, 54
	s_add_i32 s0, 0, 0x200a0
	v_writelane_b32 v253, s0, 55
	s_add_i32 s0, 0, 0x200b0
	v_writelane_b32 v253, s0, 56
	s_add_i32 s0, 0, 0x200c0
	v_writelane_b32 v253, s0, 57
	s_add_i32 s0, 0, 0x20098
	v_writelane_b32 v253, s0, 58
	s_add_i32 s0, 0, 0x20040
	v_writelane_b32 v253, s0, 59
	s_add_i32 s0, 0, 0x20038
	v_writelane_b32 v253, s0, 60
	s_add_i32 s0, 0, 0x20030
	v_writelane_b32 v253, s0, 61
	s_add_i32 s0, 0, 0x20200
	v_writelane_b32 v253, s0, 62
	s_add_i32 s0, 0, 0x20204
	v_writelane_b32 v253, s0, 63
	s_mov_b32 s75, 0x3f000
	v_readlane_b32 s0, v253, 0
	s_mov_b32 s52, s0
	s_mov_b32 s27, 0
	v_cmp_eq_u32_e64 s[0:1], 0, v0
	s_mov_b64 s[70:71], 0x200
	s_mov_b64 s[50:51], 0x80
	v_writelane_b32 v254, s0, 0
	s_nop 1
	v_writelane_b32 v254, s1, 1
	s_lshl_b64 s[0:1], s[28:29], 7
	v_writelane_b32 v254, s0, 2
	s_nop 1
	v_writelane_b32 v254, s1, 3
	s_lshl_b64 s[0:1], s[28:29], 6
	v_writelane_b32 v254, s0, 4
	s_nop 1
	v_writelane_b32 v254, s1, 5
	s_lshl_b64 s[0:1], s[28:29], 2
	v_writelane_b32 v254, s0, 6
	s_nop 1
	v_writelane_b32 v254, s1, 7
	s_lshl_b64 s[0:1], s[28:29], 1
	v_writelane_b32 v254, s0, 8
	s_nop 1
	v_writelane_b32 v254, s1, 9
	v_writelane_b32 v254, s28, 10
	s_nop 1
	v_writelane_b32 v254, s29, 11
	v_writelane_b32 v254, s30, 12
	s_nop 1
	v_writelane_b32 v254, s31, 13
	v_writelane_b32 v254, s34, 14
	s_nop 1
	v_writelane_b32 v254, s35, 15
	v_writelane_b32 v254, s36, 16
	s_nop 1
	v_writelane_b32 v254, s37, 17
	v_writelane_b32 v254, s24, 18
	s_nop 1
	v_writelane_b32 v254, s25, 19
	v_writelane_b32 v254, s16, 20
	s_nop 1
	v_writelane_b32 v254, s17, 21
	v_writelane_b32 v254, s18, 22
	s_nop 1
	v_writelane_b32 v254, s19, 23
	v_writelane_b32 v254, s20, 24
	s_nop 1
	v_writelane_b32 v254, s21, 25
	v_writelane_b32 v254, s22, 26
	s_nop 1
	v_writelane_b32 v254, s23, 27
	v_writelane_b32 v254, s64, 28
	v_writelane_b32 v254, s26, 29
	v_writelane_b32 v254, s42, 30
	s_nop 1
	v_writelane_b32 v254, s43, 31
	v_writelane_b32 v254, s46, 32
	s_nop 1
	v_writelane_b32 v254, s47, 33
	v_writelane_b32 v254, s48, 34
	s_nop 1
	v_writelane_b32 v254, s49, 35
	v_writelane_b32 v254, s60, 36
	s_nop 1
	v_writelane_b32 v254, s61, 37
	v_writelane_b32 v254, s62, 38
	s_nop 1
	v_writelane_b32 v254, s63, 39
	v_writelane_b32 v254, s72, 40
	s_nop 1
	v_writelane_b32 v254, s73, 41
	v_writelane_b32 v254, s82, 42
	s_nop 1
	v_writelane_b32 v254, s83, 43
	v_writelane_b32 v254, s84, 44
	s_nop 1
	v_writelane_b32 v254, s85, 45
	v_writelane_b32 v254, s86, 46
	s_nop 1
	v_writelane_b32 v254, s87, 47
	v_writelane_b32 v254, s88, 48
	s_nop 1
	v_writelane_b32 v254, s89, 49
	s_mov_b32 s99, 0
	s_mov_b32 s101, 0
	s_branch .LBB0_13
.Lexit_near:
	s_endpgm
.LBB0_10:
	s_or_b64 exec, exec, s[10:11]
	s_waitcnt vmcnt(0)

.LBB0_128:
	s_cmp_lg_u32 s7, 3
	s_cselect_b64 s[22:23], -1, 0
	s_lshl_b32 s8, s10, 1
	v_readlane_b32 s10, v254, 50
	v_lshl_or_b32 v70, s48, 7, v78
	v_readlane_b32 s11, v254, 51
	s_add_u32 s8, s10, s8
	s_addc_u32 s9, s11, 0
	v_ashrrev_i32_e32 v71, 31, v70
	v_lshlrev_b64 v[70:71], 1, v[70:71]
	s_cmp_eq_u32 s7, 4
	v_lshl_add_u64 v[74:75], s[8:9], 0, v[70:71]
	s_cselect_b64 s[8:9], -1, 0
	v_readlane_b32 s10, v255, 0
	s_cmp_eq_u32 s7, 0
	v_readlane_b32 s11, v255, 1
	v_cndmask_b32_e64 v73, 0, 1, s[8:9]
	v_lshl_add_u32 v72, s6, 8, v76
	s_cselect_b64 s[6:7], -1, 0
	v_lshl_add_u64 v[70:71], s[10:11], 0, v[70:71]
	s_mov_b64 s[12:13], -1
	s_and_b64 vcc, exec, s[22:23]
	v_cmp_ne_u32_e64 s[10:11], 1, v73
	s_cbranch_vccz .LBB0_132
	s_and_b64 vcc, exec, s[8:9]
	s_cbranch_vccz .Lbm_fast
	v_mad_i64_i32 v[154:155], s[12:13], v72, s2, v[74:75]
	global_load_dwordx4 v[186:189], v[154:155], off
	v_mul_f32_e32 v154, 0xbfb8aa3b, v60
	v_mul_f32_e32 v156, 0xbfb8aa3b, v61
	v_mul_f32_e32 v160, 0xbfb8aa3b, v63
	v_exp_f32_e32 v154, v154
	v_exp_f32_e32 v156, v156
	v_exp_f32_e32 v160, v160
	v_mul_f32_e32 v158, 0xbfb8aa3b, v62
	v_add_f32_e32 v154, 1.0, v154
	v_add_f32_e32 v156, 1.0, v156
	v_add_f32_e32 v160, 1.0, v160
	v_rcp_f32_e32 v154, v154
	v_rcp_f32_e32 v156, v156
	v_rcp_f32_e32 v160, v160
	v_mul_f32_e32 v192, 0xbfb8aa3b, v57
	v_lshlrev_b32_e32 v73, 16, v108
	v_mul_f32_e32 v190, 0xbfb8aa3b, v56
	v_exp_f32_e32 v158, v158
	v_exp_f32_e32 v192, v192
	v_and_b32_e32 v155, 0xffff0000, v108
	v_and_b32_e32 v159, 0xffff0000, v111
	v_exp_f32_e32 v190, v190
	v_mul_f32_e32 v73, v154, v73
	v_mul_f32_e32 v154, v156, v155
	v_mul_f32_e32 v156, v160, v159
	v_cndmask_b32_e64 v159, v60, v73, s[8:9]
	v_mul_f32_e32 v193, 0xbfb8aa3b, v58
	v_exp_f32_e32 v193, v193
	v_add_f32_e32 v158, 1.0, v158
	v_add_f32_e32 v192, 1.0, v192
	v_add_f32_e32 v190, 1.0, v190
	v_rcp_f32_e32 v158, v158
	v_rcp_f32_e32 v192, v192
	v_rcp_f32_e32 v190, v190
	v_lshlrev_b32_e32 v157, 16, v111
	v_and_b32_e32 v191, 0xffff0000, v107
	v_add_f32_e32 v197, 1.0, v193
	v_lshlrev_b32_e32 v185, 16, v107
	v_mul_f32_e32 v155, v158, v157
	v_mul_f32_e32 v158, v192, v191
	v_mul_f32_e32 v157, v190, v185
	v_lshlrev_b32_e32 v199, 16, v110
	v_cndmask_b32_e64 v154, v61, v154, s[8:9]
	v_cndmask_b32_e64 v155, v62, v155, s[8:9]
	v_cndmask_b32_e64 v156, v63, v156, s[8:9]
	v_cndmask_b32_e64 v157, v56, v157, s[8:9]
	v_cndmask_b32_e64 v158, v57, v158, s[8:9]
	s_and_b64 vcc, exec, s[10:11]
	s_waitcnt vmcnt(0)
	v_lshlrev_b32_e32 v73, 16, v186
	v_mul_f32_e32 v73, 0xbfb8aa3b, v73
	v_exp_f32_e32 v73, v73
	v_and_b32_e32 v160, 0xffff0000, v186
	v_lshlrev_b32_e32 v185, 16, v187
	v_and_b32_e32 v186, 0xffff0000, v187
	v_add_f32_e32 v73, 1.0, v73
	v_rcp_f32_e32 v191, v73
	v_rcp_f32_e32 v73, v197
	v_mul_f32_e32 v197, 0xbfb8aa3b, v59
	v_lshlrev_b32_e32 v187, 16, v188
	v_and_b32_e32 v188, 0xffff0000, v188
	v_lshlrev_b32_e32 v190, 16, v189
	v_and_b32_e32 v189, 0xffff0000, v189
	v_exp_f32_e32 v198, v197
	v_mul_f32_e32 v160, 0xbfb8aa3b, v160
	v_mul_f32_e32 v185, 0xbfb8aa3b, v185
	v_mul_f32_e32 v186, 0xbfb8aa3b, v186
	v_mul_f32_e32 v187, 0xbfb8aa3b, v187
	v_mul_f32_e32 v188, 0xbfb8aa3b, v188
	v_mul_f32_e32 v190, 0xbfb8aa3b, v190
	v_mul_f32_e32 v189, 0xbfb8aa3b, v189
	v_exp_f32_e32 v160, v160
	v_exp_f32_e32 v185, v185
	v_exp_f32_e32 v186, v186
	v_exp_f32_e32 v187, v187
	v_exp_f32_e32 v188, v188
	v_exp_f32_e32 v190, v190
	v_exp_f32_e32 v189, v189
	v_add_f32_e32 v198, 1.0, v198
	v_rcp_f32_e32 v200, v198
	v_add_f32_e32 v160, 1.0, v160
	v_add_f32_e32 v185, 1.0, v185
	v_add_f32_e32 v186, 1.0, v186
	v_add_f32_e32 v187, 1.0, v187
	v_add_f32_e32 v192, 1.0, v188
	v_add_f32_e32 v193, 1.0, v190
	v_add_f32_e32 v194, 1.0, v189
	v_rcp_f32_e32 v190, v160
	v_rcp_f32_e32 v189, v185
	v_rcp_f32_e32 v188, v186
	v_rcp_f32_e32 v187, v187
	v_rcp_f32_e32 v186, v192
	v_rcp_f32_e32 v185, v193
	v_rcp_f32_e32 v160, v194
	v_mul_f32_e32 v73, v73, v199
	v_cndmask_b32_e64 v199, v58, v73, s[8:9]
	v_and_b32_e32 v73, 0xffff0000, v110
	v_mul_f32_e32 v73, v200, v73
	v_cndmask_b32_e64 v200, v59, v73, s[8:9]
	v_fma_f32 v196, v159, v191, v181
	v_fma_f32 v195, v154, v190, v182
	v_fma_f32 v194, v155, v189, v183
	v_fma_f32 v193, v156, v188, v184
	v_fma_f32 v192, v157, v187, v177
	v_fma_f32 v197, v158, v186, v178
	v_fma_f32 v198, v199, v185, v179
	v_fma_f32 v201, v200, v160, v180
	s_cbranch_vccnz .LBB0_131
	v_ashrrev_i32_e32 v73, 31, v72
	v_lshlrev_b64 v[206:207], 11, v[72:73]
	v_cvt_pk_bf16_f32 v202, v196, v195
	v_cvt_pk_bf16_f32 v203, v194, v193
	v_cvt_pk_bf16_f32 v204, v192, v197
	v_cvt_pk_bf16_f32 v205, v198, v201
	v_lshl_add_u64 v[206:207], v[70:71], 0, v[206:207]
	global_store_dwordx4 v[206:207], v[202:205], off

.Lbm_fast:
	v_mad_i64_i32 v[248:249], s[12:13], v72, s2, v[74:75]
	global_load_dwordx4 v[208:211], v[248:249], off
	v_or_b32_e32 v250, 16, v72
	v_mad_i64_i32 v[248:249], s[12:13], v250, s2, v[74:75]
	global_load_dwordx4 v[212:215], v[248:249], off
	v_or_b32_e32 v250, 32, v72
	v_mad_i64_i32 v[248:249], s[12:13], v250, s2, v[74:75]
	global_load_dwordx4 v[216:219], v[248:249], off
	v_or_b32_e32 v250, 48, v72
	v_mad_i64_i32 v[248:249], s[12:13], v250, s2, v[74:75]
	global_load_dwordx4 v[220:223], v[248:249], off
	v_add_u32_e32 v250, 0x80, v72
	v_mad_i64_i32 v[248:249], s[12:13], v250, s2, v[74:75]
	global_load_dwordx4 v[224:227], v[248:249], off
	v_add_u32_e32 v250, 0x90, v72
	v_mad_i64_i32 v[248:249], s[12:13], v250, s2, v[74:75]
	global_load_dwordx4 v[228:231], v[248:249], off
	v_add_u32_e32 v250, 0xa0, v72
	v_mad_i64_i32 v[248:249], s[12:13], v250, s2, v[74:75]
	global_load_dwordx4 v[232:235], v[248:249], off
	v_add_u32_e32 v250, 0xb0, v72
	v_mad_i64_i32 v[248:249], s[12:13], v250, s2, v[74:75]
	global_load_dwordx4 v[240:243], v[248:249], off
	s_and_b64 vcc, exec, s[6:7]
	s_cbranch_vccnz .Lbm_fast_mul
	s_waitcnt vmcnt(7)
	v_lshlrev_b32_e32 v186, 16, v208
	v_and_b32_e32 v187, 0xffff0000, v208
	v_lshlrev_b32_e32 v188, 16, v209
	v_and_b32_e32 v189, 0xffff0000, v209
	v_lshlrev_b32_e32 v190, 16, v210
	v_and_b32_e32 v191, 0xffff0000, v210
	v_lshlrev_b32_e32 v192, 16, v211
	v_and_b32_e32 v193, 0xffff0000, v211
	v_mul_f32_e32 v186, 0xbfb8aa3b, v186
	v_mul_f32_e32 v187, 0xbfb8aa3b, v187
	v_mul_f32_e32 v188, 0xbfb8aa3b, v188
	v_mul_f32_e32 v189, 0xbfb8aa3b, v189
	v_mul_f32_e32 v190, 0xbfb8aa3b, v190
	v_mul_f32_e32 v191, 0xbfb8aa3b, v191
	v_mul_f32_e32 v192, 0xbfb8aa3b, v192
	v_mul_f32_e32 v193, 0xbfb8aa3b, v193
	v_exp_f32_e32 v186, v186
	v_exp_f32_e32 v187, v187
	v_exp_f32_e32 v188, v188
	v_exp_f32_e32 v189, v189
	v_exp_f32_e32 v190, v190
	v_exp_f32_e32 v191, v191
	v_exp_f32_e32 v192, v192
	v_exp_f32_e32 v193, v193
	v_add_f32_e32 v186, 1.0, v186
	v_add_f32_e32 v187, 1.0, v187
	v_add_f32_e32 v188, 1.0, v188
	v_add_f32_e32 v189, 1.0, v189
	v_add_f32_e32 v190, 1.0, v190
	v_add_f32_e32 v191, 1.0, v191
	v_add_f32_e32 v192, 1.0, v192
	v_add_f32_e32 v193, 1.0, v193
	v_rcp_f32_e32 v186, v186
	v_rcp_f32_e32 v187, v187
	v_rcp_f32_e32 v188, v188
	v_rcp_f32_e32 v189, v189
	v_rcp_f32_e32 v190, v190
	v_rcp_f32_e32 v191, v191
	v_rcp_f32_e32 v192, v192
	v_rcp_f32_e32 v193, v193
	v_fma_f32 v73, v60, v186, v181
	v_fma_f32 v154, v61, v187, v182
	v_fma_f32 v155, v62, v188, v183
	v_fma_f32 v156, v63, v189, v184
	v_fma_f32 v157, v56, v190, v177
	v_fma_f32 v158, v57, v191, v178
	v_fma_f32 v159, v58, v192, v179
	v_fma_f32 v160, v59, v193, v180
	s_waitcnt vmcnt(6)
	v_lshlrev_b32_e32 v186, 16, v212
	v_and_b32_e32 v187, 0xffff0000, v212
	v_lshlrev_b32_e32 v188, 16, v213
	v_and_b32_e32 v189, 0xffff0000, v213
	v_lshlrev_b32_e32 v190, 16, v214
	v_and_b32_e32 v191, 0xffff0000, v214
	v_lshlrev_b32_e32 v192, 16, v215
	v_and_b32_e32 v193, 0xffff0000, v215
	v_mul_f32_e32 v186, 0xbfb8aa3b, v186
	v_mul_f32_e32 v187, 0xbfb8aa3b, v187
	v_mul_f32_e32 v188, 0xbfb8aa3b, v188
	v_mul_f32_e32 v189, 0xbfb8aa3b, v189
	v_mul_f32_e32 v190, 0xbfb8aa3b, v190
	v_mul_f32_e32 v191, 0xbfb8aa3b, v191
	v_mul_f32_e32 v192, 0xbfb8aa3b, v192
	v_mul_f32_e32 v193, 0xbfb8aa3b, v193
	v_exp_f32_e32 v186, v186
	v_exp_f32_e32 v187, v187
	v_exp_f32_e32 v188, v188
	v_exp_f32_e32 v189, v189
	v_exp_f32_e32 v190, v190
	v_exp_f32_e32 v191, v191
	v_exp_f32_e32 v192, v192
	v_exp_f32_e32 v193, v193
	v_add_f32_e32 v186, 1.0, v186
	v_add_f32_e32 v187, 1.0, v187
	v_add_f32_e32 v188, 1.0, v188
	v_add_f32_e32 v189, 1.0, v189
	v_add_f32_e32 v190, 1.0, v190
	v_add_f32_e32 v191, 1.0, v191
	v_add_f32_e32 v192, 1.0, v192
	v_add_f32_e32 v193, 1.0, v193
	v_rcp_f32_e32 v186, v186
	v_rcp_f32_e32 v187, v187
	v_rcp_f32_e32 v188, v188
	v_rcp_f32_e32 v189, v189
	v_rcp_f32_e32 v190, v190
	v_rcp_f32_e32 v191, v191
	v_rcp_f32_e32 v192, v192
	v_rcp_f32_e32 v193, v193
	v_fma_f32 v56, v52, v186, v173
	v_fma_f32 v57, v53, v187, v174
	v_fma_f32 v58, v54, v188, v175
	v_fma_f32 v59, v55, v189, v176
	v_fma_f32 v60, v48, v190, v169
	v_fma_f32 v61, v49, v191, v170
	v_fma_f32 v62, v50, v192, v171
	v_fma_f32 v63, v51, v193, v172
	s_waitcnt vmcnt(5)
	v_lshlrev_b32_e32 v186, 16, v216
	v_and_b32_e32 v187, 0xffff0000, v216
	v_lshlrev_b32_e32 v188, 16, v217
	v_and_b32_e32 v189, 0xffff0000, v217
	v_lshlrev_b32_e32 v190, 16, v218
	v_and_b32_e32 v191, 0xffff0000, v218
	v_lshlrev_b32_e32 v192, 16, v219
	v_and_b32_e32 v193, 0xffff0000, v219
	v_mul_f32_e32 v186, 0xbfb8aa3b, v186
	v_mul_f32_e32 v187, 0xbfb8aa3b, v187
	v_mul_f32_e32 v188, 0xbfb8aa3b, v188
	v_mul_f32_e32 v189, 0xbfb8aa3b, v189
	v_mul_f32_e32 v190, 0xbfb8aa3b, v190
	v_mul_f32_e32 v191, 0xbfb8aa3b, v191
	v_mul_f32_e32 v192, 0xbfb8aa3b, v192
	v_mul_f32_e32 v193, 0xbfb8aa3b, v193
	v_exp_f32_e32 v186, v186
	v_exp_f32_e32 v187, v187
	v_exp_f32_e32 v188, v188
	v_exp_f32_e32 v189, v189
	v_exp_f32_e32 v190, v190
	v_exp_f32_e32 v191, v191
	v_exp_f32_e32 v192, v192
	v_exp_f32_e32 v193, v193
	v_add_f32_e32 v186, 1.0, v186
	v_add_f32_e32 v187, 1.0, v187
	v_add_f32_e32 v188, 1.0, v188
	v_add_f32_e32 v189, 1.0, v189
	v_add_f32_e32 v190, 1.0, v190
	v_add_f32_e32 v191, 1.0, v191
	v_add_f32_e32 v192, 1.0, v192
	v_add_f32_e32 v193, 1.0, v193
	v_rcp_f32_e32 v186, v186
	v_rcp_f32_e32 v187, v187
	v_rcp_f32_e32 v188, v188
	v_rcp_f32_e32 v189, v189
	v_rcp_f32_e32 v190, v190
	v_rcp_f32_e32 v191, v191
	v_rcp_f32_e32 v192, v192
	v_rcp_f32_e32 v193, v193
	v_fma_f32 v48, v44, v186, v165
	v_fma_f32 v49, v45, v187, v166
	v_fma_f32 v50, v46, v188, v167
	v_fma_f32 v51, v47, v189, v168
	v_fma_f32 v52, v40, v190, v161
	v_fma_f32 v53, v41, v191, v162
	v_fma_f32 v54, v42, v192, v163
	v_fma_f32 v55, v43, v193, v164
	s_waitcnt vmcnt(4)
	v_lshlrev_b32_e32 v186, 16, v220
	v_and_b32_e32 v187, 0xffff0000, v220
	v_lshlrev_b32_e32 v188, 16, v221
	v_and_b32_e32 v189, 0xffff0000, v221
	v_lshlrev_b32_e32 v190, 16, v222
	v_and_b32_e32 v191, 0xffff0000, v222
	v_lshlrev_b32_e32 v192, 16, v223
	v_and_b32_e32 v193, 0xffff0000, v223
	v_mul_f32_e32 v186, 0xbfb8aa3b, v186
	v_mul_f32_e32 v187, 0xbfb8aa3b, v187
	v_mul_f32_e32 v188, 0xbfb8aa3b, v188
	v_mul_f32_e32 v189, 0xbfb8aa3b, v189
	v_mul_f32_e32 v190, 0xbfb8aa3b, v190
	v_mul_f32_e32 v191, 0xbfb8aa3b, v191
	v_mul_f32_e32 v192, 0xbfb8aa3b, v192
	v_mul_f32_e32 v193, 0xbfb8aa3b, v193
	v_exp_f32_e32 v186, v186
	v_exp_f32_e32 v187, v187
	v_exp_f32_e32 v188, v188
	v_exp_f32_e32 v189, v189
	v_exp_f32_e32 v190, v190
	v_exp_f32_e32 v191, v191
	v_exp_f32_e32 v192, v192
	v_exp_f32_e32 v193, v193
	v_add_f32_e32 v186, 1.0, v186
	v_add_f32_e32 v187, 1.0, v187
	v_add_f32_e32 v188, 1.0, v188
	v_add_f32_e32 v189, 1.0, v189
	v_add_f32_e32 v190, 1.0, v190
	v_add_f32_e32 v191, 1.0, v191
	v_add_f32_e32 v192, 1.0, v192
	v_add_f32_e32 v193, 1.0, v193
	v_rcp_f32_e32 v186, v186
	v_rcp_f32_e32 v187, v187
	v_rcp_f32_e32 v188, v188
	v_rcp_f32_e32 v189, v189
	v_rcp_f32_e32 v190, v190
	v_rcp_f32_e32 v191, v191
	v_rcp_f32_e32 v192, v192
	v_rcp_f32_e32 v193, v193
	v_fma_f32 v40, v36, v186, v150
	v_fma_f32 v41, v37, v187, v151
	v_fma_f32 v42, v38, v188, v152
	v_fma_f32 v43, v39, v189, v153
	v_fma_f32 v44, v32, v190, v146
	v_fma_f32 v45, v33, v191, v147
	v_fma_f32 v46, v34, v192, v148
	v_fma_f32 v47, v35, v193, v149
	s_waitcnt vmcnt(3)
	v_lshlrev_b32_e32 v186, 16, v224
	v_and_b32_e32 v187, 0xffff0000, v224
	v_lshlrev_b32_e32 v188, 16, v225
	v_and_b32_e32 v189, 0xffff0000, v225
	v_lshlrev_b32_e32 v190, 16, v226
	v_and_b32_e32 v191, 0xffff0000, v226
	v_lshlrev_b32_e32 v192, 16, v227
	v_and_b32_e32 v193, 0xffff0000, v227
	v_mul_f32_e32 v186, 0xbfb8aa3b, v186
	v_mul_f32_e32 v187, 0xbfb8aa3b, v187
	v_mul_f32_e32 v188, 0xbfb8aa3b, v188
	v_mul_f32_e32 v189, 0xbfb8aa3b, v189
	v_mul_f32_e32 v190, 0xbfb8aa3b, v190
	v_mul_f32_e32 v191, 0xbfb8aa3b, v191
	v_mul_f32_e32 v192, 0xbfb8aa3b, v192
	v_mul_f32_e32 v193, 0xbfb8aa3b, v193
	v_exp_f32_e32 v186, v186
	v_exp_f32_e32 v187, v187
	v_exp_f32_e32 v188, v188
	v_exp_f32_e32 v189, v189
	v_exp_f32_e32 v190, v190
	v_exp_f32_e32 v191, v191
	v_exp_f32_e32 v192, v192
	v_exp_f32_e32 v193, v193
	v_add_f32_e32 v186, 1.0, v186
	v_add_f32_e32 v187, 1.0, v187
	v_add_f32_e32 v188, 1.0, v188
	v_add_f32_e32 v189, 1.0, v189
	v_add_f32_e32 v190, 1.0, v190
	v_add_f32_e32 v191, 1.0, v191
	v_add_f32_e32 v192, 1.0, v192
	v_add_f32_e32 v193, 1.0, v193
	v_rcp_f32_e32 v186, v186
	v_rcp_f32_e32 v187, v187
	v_rcp_f32_e32 v188, v188
	v_rcp_f32_e32 v189, v189
	v_rcp_f32_e32 v190, v190
	v_rcp_f32_e32 v191, v191
	v_rcp_f32_e32 v192, v192
	v_rcp_f32_e32 v193, v193
	v_fma_f32 v32, v28, v186, v140
	v_fma_f32 v33, v29, v187, v141
	v_fma_f32 v34, v30, v188, v142
	v_fma_f32 v35, v31, v189, v143
	v_fma_f32 v36, v24, v190, v136
	v_fma_f32 v37, v25, v191, v137
	v_fma_f32 v38, v26, v192, v138
	v_fma_f32 v39, v27, v193, v139
	s_waitcnt vmcnt(2)
	v_lshlrev_b32_e32 v186, 16, v228
	v_and_b32_e32 v187, 0xffff0000, v228
	v_lshlrev_b32_e32 v188, 16, v229
	v_and_b32_e32 v189, 0xffff0000, v229
	v_lshlrev_b32_e32 v190, 16, v230
	v_and_b32_e32 v191, 0xffff0000, v230
	v_lshlrev_b32_e32 v192, 16, v231
	v_and_b32_e32 v193, 0xffff0000, v231
	v_mul_f32_e32 v186, 0xbfb8aa3b, v186
	v_mul_f32_e32 v187, 0xbfb8aa3b, v187
	v_mul_f32_e32 v188, 0xbfb8aa3b, v188
	v_mul_f32_e32 v189, 0xbfb8aa3b, v189
	v_mul_f32_e32 v190, 0xbfb8aa3b, v190
	v_mul_f32_e32 v191, 0xbfb8aa3b, v191
	v_mul_f32_e32 v192, 0xbfb8aa3b, v192
	v_mul_f32_e32 v193, 0xbfb8aa3b, v193
	v_exp_f32_e32 v186, v186
	v_exp_f32_e32 v187, v187
	v_exp_f32_e32 v188, v188
	v_exp_f32_e32 v189, v189
	v_exp_f32_e32 v190, v190
	v_exp_f32_e32 v191, v191
	v_exp_f32_e32 v192, v192
	v_exp_f32_e32 v193, v193
	v_add_f32_e32 v186, 1.0, v186
	v_add_f32_e32 v187, 1.0, v187
	v_add_f32_e32 v188, 1.0, v188
	v_add_f32_e32 v189, 1.0, v189
	v_add_f32_e32 v190, 1.0, v190
	v_add_f32_e32 v191, 1.0, v191
	v_add_f32_e32 v192, 1.0, v192
	v_add_f32_e32 v193, 1.0, v193
	v_rcp_f32_e32 v186, v186
	v_rcp_f32_e32 v187, v187
	v_rcp_f32_e32 v188, v188
	v_rcp_f32_e32 v189, v189
	v_rcp_f32_e32 v190, v190
	v_rcp_f32_e32 v191, v191
	v_rcp_f32_e32 v192, v192
	v_rcp_f32_e32 v193, v193
	v_fma_f32 v24, v20, v186, v132
	v_fma_f32 v25, v21, v187, v133
	v_fma_f32 v26, v22, v188, v134
	v_fma_f32 v27, v23, v189, v135
	v_fma_f32 v28, v16, v190, v128
	v_fma_f32 v29, v17, v191, v129
	v_fma_f32 v30, v18, v192, v130
	v_fma_f32 v31, v19, v193, v131
	s_waitcnt vmcnt(1)
	v_lshlrev_b32_e32 v186, 16, v232
	v_and_b32_e32 v187, 0xffff0000, v232
	v_lshlrev_b32_e32 v188, 16, v233
	v_and_b32_e32 v189, 0xffff0000, v233
	v_lshlrev_b32_e32 v190, 16, v234
	v_and_b32_e32 v191, 0xffff0000, v234
	v_lshlrev_b32_e32 v192, 16, v235
	v_and_b32_e32 v193, 0xffff0000, v235
	v_mul_f32_e32 v186, 0xbfb8aa3b, v186
	v_mul_f32_e32 v187, 0xbfb8aa3b, v187
	v_mul_f32_e32 v188, 0xbfb8aa3b, v188
	v_mul_f32_e32 v189, 0xbfb8aa3b, v189
	v_mul_f32_e32 v190, 0xbfb8aa3b, v190
	v_mul_f32_e32 v191, 0xbfb8aa3b, v191
	v_mul_f32_e32 v192, 0xbfb8aa3b, v192
	v_mul_f32_e32 v193, 0xbfb8aa3b, v193
	v_exp_f32_e32 v186, v186
	v_exp_f32_e32 v187, v187
	v_exp_f32_e32 v188, v188
	v_exp_f32_e32 v189, v189
	v_exp_f32_e32 v190, v190
	v_exp_f32_e32 v191, v191
	v_exp_f32_e32 v192, v192
	v_exp_f32_e32 v193, v193
	v_add_f32_e32 v186, 1.0, v186
	v_add_f32_e32 v187, 1.0, v187
	v_add_f32_e32 v188, 1.0, v188
	v_add_f32_e32 v189, 1.0, v189
	v_add_f32_e32 v190, 1.0, v190
	v_add_f32_e32 v191, 1.0, v191
	v_add_f32_e32 v192, 1.0, v192
	v_add_f32_e32 v193, 1.0, v193
	v_rcp_f32_e32 v186, v186
	v_rcp_f32_e32 v187, v187
	v_rcp_f32_e32 v188, v188
	v_rcp_f32_e32 v189, v189
	v_rcp_f32_e32 v190, v190
	v_rcp_f32_e32 v191, v191
	v_rcp_f32_e32 v192, v192
	v_rcp_f32_e32 v193, v193
	v_fma_f32 v16, v12, v186, v124
	v_fma_f32 v17, v13, v187, v125
	v_fma_f32 v18, v14, v188, v126
	v_fma_f32 v19, v15, v189, v127
	v_fma_f32 v20, v8, v190, v120
	v_fma_f32 v21, v9, v191, v121
	v_fma_f32 v22, v10, v192, v122
	v_fma_f32 v23, v11, v193, v123
	s_waitcnt vmcnt(0)
	v_lshlrev_b32_e32 v186, 16, v240
	v_and_b32_e32 v187, 0xffff0000, v240
	v_lshlrev_b32_e32 v188, 16, v241
	v_and_b32_e32 v189, 0xffff0000, v241
	v_lshlrev_b32_e32 v190, 16, v242
	v_and_b32_e32 v191, 0xffff0000, v242
	v_lshlrev_b32_e32 v192, 16, v243
	v_and_b32_e32 v193, 0xffff0000, v243
	v_mul_f32_e32 v186, 0xbfb8aa3b, v186
	v_mul_f32_e32 v187, 0xbfb8aa3b, v187
	v_mul_f32_e32 v188, 0xbfb8aa3b, v188
	v_mul_f32_e32 v189, 0xbfb8aa3b, v189
	v_mul_f32_e32 v190, 0xbfb8aa3b, v190
	v_mul_f32_e32 v191, 0xbfb8aa3b, v191
	v_mul_f32_e32 v192, 0xbfb8aa3b, v192
	v_mul_f32_e32 v193, 0xbfb8aa3b, v193
	v_exp_f32_e32 v186, v186
	v_exp_f32_e32 v187, v187
	v_exp_f32_e32 v188, v188
	v_exp_f32_e32 v189, v189
	v_exp_f32_e32 v190, v190
	v_exp_f32_e32 v191, v191
	v_exp_f32_e32 v192, v192
	v_exp_f32_e32 v193, v193
	v_add_f32_e32 v186, 1.0, v186
	v_add_f32_e32 v187, 1.0, v187
	v_add_f32_e32 v188, 1.0, v188
	v_add_f32_e32 v189, 1.0, v189
	v_add_f32_e32 v190, 1.0, v190
	v_add_f32_e32 v191, 1.0, v191
	v_add_f32_e32 v192, 1.0, v192
	v_add_f32_e32 v193, 1.0, v193
	v_rcp_f32_e32 v186, v186
	v_rcp_f32_e32 v187, v187
	v_rcp_f32_e32 v188, v188
	v_rcp_f32_e32 v189, v189
	v_rcp_f32_e32 v190, v190
	v_rcp_f32_e32 v191, v191
	v_rcp_f32_e32 v192, v192
	v_rcp_f32_e32 v193, v193
	v_fma_f32 v8, v4, v186, v116
	v_fma_f32 v9, v5, v187, v117
	v_fma_f32 v10, v6, v188, v118
	v_fma_f32 v11, v7, v189, v119
	v_fma_f32 v12, v0, v190, v112
	v_fma_f32 v13, v1, v191, v113
	v_fma_f32 v14, v2, v192, v114
	v_fma_f32 v15, v3, v193, v115
	s_branch .LBB0_174
.Lbm_fast_mul:
	s_waitcnt vmcnt(7)
	v_lshlrev_b32_e32 v186, 16, v208
	v_and_b32_e32 v187, 0xffff0000, v208
	v_lshlrev_b32_e32 v188, 16, v209
	v_and_b32_e32 v189, 0xffff0000, v209
	v_lshlrev_b32_e32 v190, 16, v210
	v_and_b32_e32 v191, 0xffff0000, v210
	v_lshlrev_b32_e32 v192, 16, v211
	v_and_b32_e32 v193, 0xffff0000, v211
	v_mul_f32_e32 v186, 0xbfb8aa3b, v186
	v_mul_f32_e32 v187, 0xbfb8aa3b, v187
	v_mul_f32_e32 v188, 0xbfb8aa3b, v188
	v_mul_f32_e32 v189, 0xbfb8aa3b, v189
	v_mul_f32_e32 v190, 0xbfb8aa3b, v190
	v_mul_f32_e32 v191, 0xbfb8aa3b, v191
	v_mul_f32_e32 v192, 0xbfb8aa3b, v192
	v_mul_f32_e32 v193, 0xbfb8aa3b, v193
	v_exp_f32_e32 v186, v186
	v_exp_f32_e32 v187, v187
	v_exp_f32_e32 v188, v188
	v_exp_f32_e32 v189, v189
	v_exp_f32_e32 v190, v190
	v_exp_f32_e32 v191, v191
	v_exp_f32_e32 v192, v192
	v_exp_f32_e32 v193, v193
	v_add_f32_e32 v186, 1.0, v186
	v_add_f32_e32 v187, 1.0, v187
	v_add_f32_e32 v188, 1.0, v188
	v_add_f32_e32 v189, 1.0, v189
	v_add_f32_e32 v190, 1.0, v190
	v_add_f32_e32 v191, 1.0, v191
	v_add_f32_e32 v192, 1.0, v192
	v_add_f32_e32 v193, 1.0, v193
	v_rcp_f32_e32 v186, v186
	v_rcp_f32_e32 v187, v187
	v_rcp_f32_e32 v188, v188
	v_rcp_f32_e32 v189, v189
	v_rcp_f32_e32 v190, v190
	v_rcp_f32_e32 v191, v191
	v_rcp_f32_e32 v192, v192
	v_rcp_f32_e32 v193, v193
	v_mul_f32_e32 v73, v60, v186
	v_mul_f32_e32 v154, v61, v187
	v_mul_f32_e32 v155, v62, v188
	v_mul_f32_e32 v156, v63, v189
	v_mul_f32_e32 v157, v56, v190
	v_mul_f32_e32 v158, v57, v191
	v_mul_f32_e32 v159, v58, v192
	v_mul_f32_e32 v160, v59, v193
	s_waitcnt vmcnt(6)
	v_lshlrev_b32_e32 v186, 16, v212
	v_and_b32_e32 v187, 0xffff0000, v212
	v_lshlrev_b32_e32 v188, 16, v213
	v_and_b32_e32 v189, 0xffff0000, v213
	v_lshlrev_b32_e32 v190, 16, v214
	v_and_b32_e32 v191, 0xffff0000, v214
	v_lshlrev_b32_e32 v192, 16, v215
	v_and_b32_e32 v193, 0xffff0000, v215
	v_mul_f32_e32 v186, 0xbfb8aa3b, v186
	v_mul_f32_e32 v187, 0xbfb8aa3b, v187
	v_mul_f32_e32 v188, 0xbfb8aa3b, v188
	v_mul_f32_e32 v189, 0xbfb8aa3b, v189
	v_mul_f32_e32 v190, 0xbfb8aa3b, v190
	v_mul_f32_e32 v191, 0xbfb8aa3b, v191
	v_mul_f32_e32 v192, 0xbfb8aa3b, v192
	v_mul_f32_e32 v193, 0xbfb8aa3b, v193
	v_exp_f32_e32 v186, v186
	v_exp_f32_e32 v187, v187
	v_exp_f32_e32 v188, v188
	v_exp_f32_e32 v189, v189
	v_exp_f32_e32 v190, v190
	v_exp_f32_e32 v191, v191
	v_exp_f32_e32 v192, v192
	v_exp_f32_e32 v193, v193
	v_add_f32_e32 v186, 1.0, v186
	v_add_f32_e32 v187, 1.0, v187
	v_add_f32_e32 v188, 1.0, v188
	v_add_f32_e32 v189, 1.0, v189
	v_add_f32_e32 v190, 1.0, v190
	v_add_f32_e32 v191, 1.0, v191
	v_add_f32_e32 v192, 1.0, v192
	v_add_f32_e32 v193, 1.0, v193
	v_rcp_f32_e32 v186, v186
	v_rcp_f32_e32 v187, v187
	v_rcp_f32_e32 v188, v188
	v_rcp_f32_e32 v189, v189
	v_rcp_f32_e32 v190, v190
	v_rcp_f32_e32 v191, v191
	v_rcp_f32_e32 v192, v192
	v_rcp_f32_e32 v193, v193
	v_mul_f32_e32 v56, v52, v186
	v_mul_f32_e32 v57, v53, v187
	v_mul_f32_e32 v58, v54, v188
	v_mul_f32_e32 v59, v55, v189
	v_mul_f32_e32 v60, v48, v190
	v_mul_f32_e32 v61, v49, v191
	v_mul_f32_e32 v62, v50, v192
	v_mul_f32_e32 v63, v51, v193
	s_waitcnt vmcnt(5)
	v_lshlrev_b32_e32 v186, 16, v216
	v_and_b32_e32 v187, 0xffff0000, v216
	v_lshlrev_b32_e32 v188, 16, v217
	v_and_b32_e32 v189, 0xffff0000, v217
	v_lshlrev_b32_e32 v190, 16, v218
	v_and_b32_e32 v191, 0xffff0000, v218
	v_lshlrev_b32_e32 v192, 16, v219
	v_and_b32_e32 v193, 0xffff0000, v219
	v_mul_f32_e32 v186, 0xbfb8aa3b, v186
	v_mul_f32_e32 v187, 0xbfb8aa3b, v187
	v_mul_f32_e32 v188, 0xbfb8aa3b, v188
	v_mul_f32_e32 v189, 0xbfb8aa3b, v189
	v_mul_f32_e32 v190, 0xbfb8aa3b, v190
	v_mul_f32_e32 v191, 0xbfb8aa3b, v191
	v_mul_f32_e32 v192, 0xbfb8aa3b, v192
	v_mul_f32_e32 v193, 0xbfb8aa3b, v193
	v_exp_f32_e32 v186, v186
	v_exp_f32_e32 v187, v187
	v_exp_f32_e32 v188, v188
	v_exp_f32_e32 v189, v189
	v_exp_f32_e32 v190, v190
	v_exp_f32_e32 v191, v191
	v_exp_f32_e32 v192, v192
	v_exp_f32_e32 v193, v193
	v_add_f32_e32 v186, 1.0, v186
	v_add_f32_e32 v187, 1.0, v187
	v_add_f32_e32 v188, 1.0, v188
	v_add_f32_e32 v189, 1.0, v189
	v_add_f32_e32 v190, 1.0, v190
	v_add_f32_e32 v191, 1.0, v191
	v_add_f32_e32 v192, 1.0, v192
	v_add_f32_e32 v193, 1.0, v193
	v_rcp_f32_e32 v186, v186
	v_rcp_f32_e32 v187, v187
	v_rcp_f32_e32 v188, v188
	v_rcp_f32_e32 v189, v189
	v_rcp_f32_e32 v190, v190
	v_rcp_f32_e32 v191, v191
	v_rcp_f32_e32 v192, v192
	v_rcp_f32_e32 v193, v193
	v_mul_f32_e32 v48, v44, v186
	v_mul_f32_e32 v49, v45, v187
	v_mul_f32_e32 v50, v46, v188
	v_mul_f32_e32 v51, v47, v189
	v_mul_f32_e32 v52, v40, v190
	v_mul_f32_e32 v53, v41, v191
	v_mul_f32_e32 v54, v42, v192
	v_mul_f32_e32 v55, v43, v193
	s_waitcnt vmcnt(4)
	v_lshlrev_b32_e32 v186, 16, v220
	v_and_b32_e32 v187, 0xffff0000, v220
	v_lshlrev_b32_e32 v188, 16, v221
	v_and_b32_e32 v189, 0xffff0000, v221
	v_lshlrev_b32_e32 v190, 16, v222
	v_and_b32_e32 v191, 0xffff0000, v222
	v_lshlrev_b32_e32 v192, 16, v223
	v_and_b32_e32 v193, 0xffff0000, v223
	v_mul_f32_e32 v186, 0xbfb8aa3b, v186
	v_mul_f32_e32 v187, 0xbfb8aa3b, v187
	v_mul_f32_e32 v188, 0xbfb8aa3b, v188
	v_mul_f32_e32 v189, 0xbfb8aa3b, v189
	v_mul_f32_e32 v190, 0xbfb8aa3b, v190
	v_mul_f32_e32 v191, 0xbfb8aa3b, v191
	v_mul_f32_e32 v192, 0xbfb8aa3b, v192
	v_mul_f32_e32 v193, 0xbfb8aa3b, v193
	v_exp_f32_e32 v186, v186
	v_exp_f32_e32 v187, v187
	v_exp_f32_e32 v188, v188
	v_exp_f32_e32 v189, v189
	v_exp_f32_e32 v190, v190
	v_exp_f32_e32 v191, v191
	v_exp_f32_e32 v192, v192
	v_exp_f32_e32 v193, v193
	v_add_f32_e32 v186, 1.0, v186
	v_add_f32_e32 v187, 1.0, v187
	v_add_f32_e32 v188, 1.0, v188
	v_add_f32_e32 v189, 1.0, v189
	v_add_f32_e32 v190, 1.0, v190
	v_add_f32_e32 v191, 1.0, v191
	v_add_f32_e32 v192, 1.0, v192
	v_add_f32_e32 v193, 1.0, v193
	v_rcp_f32_e32 v186, v186
	v_rcp_f32_e32 v187, v187
	v_rcp_f32_e32 v188, v188
	v_rcp_f32_e32 v189, v189
	v_rcp_f32_e32 v190, v190
	v_rcp_f32_e32 v191, v191
	v_rcp_f32_e32 v192, v192
	v_rcp_f32_e32 v193, v193
	v_mul_f32_e32 v40, v36, v186
	v_mul_f32_e32 v41, v37, v187
	v_mul_f32_e32 v42, v38, v188
	v_mul_f32_e32 v43, v39, v189
	v_mul_f32_e32 v44, v32, v190
	v_mul_f32_e32 v45, v33, v191
	v_mul_f32_e32 v46, v34, v192
	v_mul_f32_e32 v47, v35, v193
	s_waitcnt vmcnt(3)
	v_lshlrev_b32_e32 v186, 16, v224
	v_and_b32_e32 v187, 0xffff0000, v224
	v_lshlrev_b32_e32 v188, 16, v225
	v_and_b32_e32 v189, 0xffff0000, v225
	v_lshlrev_b32_e32 v190, 16, v226
	v_and_b32_e32 v191, 0xffff0000, v226
	v_lshlrev_b32_e32 v192, 16, v227
	v_and_b32_e32 v193, 0xffff0000, v227
	v_mul_f32_e32 v186, 0xbfb8aa3b, v186
	v_mul_f32_e32 v187, 0xbfb8aa3b, v187
	v_mul_f32_e32 v188, 0xbfb8aa3b, v188
	v_mul_f32_e32 v189, 0xbfb8aa3b, v189
	v_mul_f32_e32 v190, 0xbfb8aa3b, v190
	v_mul_f32_e32 v191, 0xbfb8aa3b, v191
	v_mul_f32_e32 v192, 0xbfb8aa3b, v192
	v_mul_f32_e32 v193, 0xbfb8aa3b, v193
	v_exp_f32_e32 v186, v186
	v_exp_f32_e32 v187, v187
	v_exp_f32_e32 v188, v188
	v_exp_f32_e32 v189, v189
	v_exp_f32_e32 v190, v190
	v_exp_f32_e32 v191, v191
	v_exp_f32_e32 v192, v192
	v_exp_f32_e32 v193, v193
	v_add_f32_e32 v186, 1.0, v186
	v_add_f32_e32 v187, 1.0, v187
	v_add_f32_e32 v188, 1.0, v188
	v_add_f32_e32 v189, 1.0, v189
	v_add_f32_e32 v190, 1.0, v190
	v_add_f32_e32 v191, 1.0, v191
	v_add_f32_e32 v192, 1.0, v192
	v_add_f32_e32 v193, 1.0, v193
	v_rcp_f32_e32 v186, v186
	v_rcp_f32_e32 v187, v187
	v_rcp_f32_e32 v188, v188
	v_rcp_f32_e32 v189, v189
	v_rcp_f32_e32 v190, v190
	v_rcp_f32_e32 v191, v191
	v_rcp_f32_e32 v192, v192
	v_rcp_f32_e32 v193, v193
	v_mul_f32_e32 v32, v28, v186
	v_mul_f32_e32 v33, v29, v187
	v_mul_f32_e32 v34, v30, v188
	v_mul_f32_e32 v35, v31, v189
	v_mul_f32_e32 v36, v24, v190
	v_mul_f32_e32 v37, v25, v191
	v_mul_f32_e32 v38, v26, v192
	v_mul_f32_e32 v39, v27, v193
	s_waitcnt vmcnt(2)
	v_lshlrev_b32_e32 v186, 16, v228
	v_and_b32_e32 v187, 0xffff0000, v228
	v_lshlrev_b32_e32 v188, 16, v229
	v_and_b32_e32 v189, 0xffff0000, v229
	v_lshlrev_b32_e32 v190, 16, v230
	v_and_b32_e32 v191, 0xffff0000, v230
	v_lshlrev_b32_e32 v192, 16, v231
	v_and_b32_e32 v193, 0xffff0000, v231
	v_mul_f32_e32 v186, 0xbfb8aa3b, v186
	v_mul_f32_e32 v187, 0xbfb8aa3b, v187
	v_mul_f32_e32 v188, 0xbfb8aa3b, v188
	v_mul_f32_e32 v189, 0xbfb8aa3b, v189
	v_mul_f32_e32 v190, 0xbfb8aa3b, v190
	v_mul_f32_e32 v191, 0xbfb8aa3b, v191
	v_mul_f32_e32 v192, 0xbfb8aa3b, v192
	v_mul_f32_e32 v193, 0xbfb8aa3b, v193
	v_exp_f32_e32 v186, v186
	v_exp_f32_e32 v187, v187
	v_exp_f32_e32 v188, v188
	v_exp_f32_e32 v189, v189
	v_exp_f32_e32 v190, v190
	v_exp_f32_e32 v191, v191
	v_exp_f32_e32 v192, v192
	v_exp_f32_e32 v193, v193
	v_add_f32_e32 v186, 1.0, v186
	v_add_f32_e32 v187, 1.0, v187
	v_add_f32_e32 v188, 1.0, v188
	v_add_f32_e32 v189, 1.0, v189
	v_add_f32_e32 v190, 1.0, v190
	v_add_f32_e32 v191, 1.0, v191
	v_add_f32_e32 v192, 1.0, v192
	v_add_f32_e32 v193, 1.0, v193
	v_rcp_f32_e32 v186, v186
	v_rcp_f32_e32 v187, v187
	v_rcp_f32_e32 v188, v188
	v_rcp_f32_e32 v189, v189
	v_rcp_f32_e32 v190, v190
	v_rcp_f32_e32 v191, v191
	v_rcp_f32_e32 v192, v192
	v_rcp_f32_e32 v193, v193
	v_mul_f32_e32 v24, v20, v186
	v_mul_f32_e32 v25, v21, v187
	v_mul_f32_e32 v26, v22, v188
	v_mul_f32_e32 v27, v23, v189
	v_mul_f32_e32 v28, v16, v190
	v_mul_f32_e32 v29, v17, v191
	v_mul_f32_e32 v30, v18, v192
	v_mul_f32_e32 v31, v19, v193
	s_waitcnt vmcnt(1)
	v_lshlrev_b32_e32 v186, 16, v232
	v_and_b32_e32 v187, 0xffff0000, v232
	v_lshlrev_b32_e32 v188, 16, v233
	v_and_b32_e32 v189, 0xffff0000, v233
	v_lshlrev_b32_e32 v190, 16, v234
	v_and_b32_e32 v191, 0xffff0000, v234
	v_lshlrev_b32_e32 v192, 16, v235
	v_and_b32_e32 v193, 0xffff0000, v235
	v_mul_f32_e32 v186, 0xbfb8aa3b, v186
	v_mul_f32_e32 v187, 0xbfb8aa3b, v187
	v_mul_f32_e32 v188, 0xbfb8aa3b, v188
	v_mul_f32_e32 v189, 0xbfb8aa3b, v189
	v_mul_f32_e32 v190, 0xbfb8aa3b, v190
	v_mul_f32_e32 v191, 0xbfb8aa3b, v191
	v_mul_f32_e32 v192, 0xbfb8aa3b, v192
	v_mul_f32_e32 v193, 0xbfb8aa3b, v193
	v_exp_f32_e32 v186, v186
	v_exp_f32_e32 v187, v187
	v_exp_f32_e32 v188, v188
	v_exp_f32_e32 v189, v189
	v_exp_f32_e32 v190, v190
	v_exp_f32_e32 v191, v191
	v_exp_f32_e32 v192, v192
	v_exp_f32_e32 v193, v193
	v_add_f32_e32 v186, 1.0, v186
	v_add_f32_e32 v187, 1.0, v187
	v_add_f32_e32 v188, 1.0, v188
	v_add_f32_e32 v189, 1.0, v189
	v_add_f32_e32 v190, 1.0, v190
	v_add_f32_e32 v191, 1.0, v191
	v_add_f32_e32 v192, 1.0, v192
	v_add_f32_e32 v193, 1.0, v193
	v_rcp_f32_e32 v186, v186
	v_rcp_f32_e32 v187, v187
	v_rcp_f32_e32 v188, v188
	v_rcp_f32_e32 v189, v189
	v_rcp_f32_e32 v190, v190
	v_rcp_f32_e32 v191, v191
	v_rcp_f32_e32 v192, v192
	v_rcp_f32_e32 v193, v193
	v_mul_f32_e32 v16, v12, v186
	v_mul_f32_e32 v17, v13, v187
	v_mul_f32_e32 v18, v14, v188
	v_mul_f32_e32 v19, v15, v189
	v_mul_f32_e32 v20, v8, v190
	v_mul_f32_e32 v21, v9, v191
	v_mul_f32_e32 v22, v10, v192
	v_mul_f32_e32 v23, v11, v193
	s_waitcnt vmcnt(0)
	v_lshlrev_b32_e32 v186, 16, v240
	v_and_b32_e32 v187, 0xffff0000, v240
	v_lshlrev_b32_e32 v188, 16, v241
	v_and_b32_e32 v189, 0xffff0000, v241
	v_lshlrev_b32_e32 v190, 16, v242
	v_and_b32_e32 v191, 0xffff0000, v242
	v_lshlrev_b32_e32 v192, 16, v243
	v_and_b32_e32 v193, 0xffff0000, v243
	v_mul_f32_e32 v186, 0xbfb8aa3b, v186
	v_mul_f32_e32 v187, 0xbfb8aa3b, v187
	v_mul_f32_e32 v188, 0xbfb8aa3b, v188
	v_mul_f32_e32 v189, 0xbfb8aa3b, v189
	v_mul_f32_e32 v190, 0xbfb8aa3b, v190
	v_mul_f32_e32 v191, 0xbfb8aa3b, v191
	v_mul_f32_e32 v192, 0xbfb8aa3b, v192
	v_mul_f32_e32 v193, 0xbfb8aa3b, v193
	v_exp_f32_e32 v186, v186
	v_exp_f32_e32 v187, v187
	v_exp_f32_e32 v188, v188
	v_exp_f32_e32 v189, v189
	v_exp_f32_e32 v190, v190
	v_exp_f32_e32 v191, v191
	v_exp_f32_e32 v192, v192
	v_exp_f32_e32 v193, v193
	v_add_f32_e32 v186, 1.0, v186
	v_add_f32_e32 v187, 1.0, v187
	v_add_f32_e32 v188, 1.0, v188
	v_add_f32_e32 v189, 1.0, v189
	v_add_f32_e32 v190, 1.0, v190
	v_add_f32_e32 v191, 1.0, v191
	v_add_f32_e32 v192, 1.0, v192
	v_add_f32_e32 v193, 1.0, v193
	v_rcp_f32_e32 v186, v186
	v_rcp_f32_e32 v187, v187
	v_rcp_f32_e32 v188, v188
	v_rcp_f32_e32 v189, v189
	v_rcp_f32_e32 v190, v190
	v_rcp_f32_e32 v191, v191
	v_rcp_f32_e32 v192, v192
	v_rcp_f32_e32 v193, v193
	v_mul_f32_e32 v8, v4, v186
	v_mul_f32_e32 v9, v5, v187
	v_mul_f32_e32 v10, v6, v188
	v_mul_f32_e32 v11, v7, v189
	v_mul_f32_e32 v12, v0, v190
	v_mul_f32_e32 v13, v1, v191
	v_mul_f32_e32 v14, v2, v192
	v_mul_f32_e32 v15, v3, v193
	s_branch .LBB0_174
